# code placement: first five GEMM loops moved by 4 bytes (never-executed padding), scan body and later loops at the same byte phase as v36
# baseline (speedup 1.0000x reference)
; #define PH_BEGIN const int zi = opaque0(); unsigned char* ws = P.ws + zi; float* const OUT = P.out + zi; (void)OUT; const int tid = opqv((int)threadIdx.x); const int bid = opqs((int)blockIdx.x); const int G = opqs((int)gridDim.x); (void)tid; (void)bid; (void)G; unsigned char* WB = ws + WS_WB; float* SS = (float*)(ws + WS_SS); (void)WB; (void)SS; (void)zi;
; __global__ void __launch_bounds__(512) mega(Params P) {
;     ...
;     for (int ph = 0; ph < NL * 12 + 1; ++ph) {
;         const int l = ph / 12, kph = ph - l * 12;
;         if (kph == 7 && ph != NL * 12) continue;
;         if (ph == NL * 12) {
;     ...
;     { PH_BEGIN
;         const int lane = tid & 63, gw = bid * 8 + (tid >> 6), nw = G * 8;
;         const float* fn = INP(32); const float* ssf = SS + (size_t)0 * T * 16; float* X = OUT;
;         for (int r = gw; r < T; r += nw) { const float rs = row_rstd(ssf, r);
; #pragma unroll
;             for (int i = 0; i < 4; ++i) { const size_t o = (size_t)r * D + i * 256 + lane * 4; *(f32x4*)(X + o) = *(const f32x4*)(X + o) * rs * *(const f32x4*)(fn + i * 256 + lane * 4); } }
;     }
;     ...
;             break;
;         }
;         switch (kph) {
.Lpost_getpc1:
	s_add_u32 s98, s98, (.LBB0_854-.Lpost_getpc1)&4294967295
	s_addc_u32 s99, s99, (.LBB0_854-.Lpost_getpc1)>>32
	s_setpc_b64 s[98:99]
	s_nop 0

; __device__ __forceinline__ void gla_gcum(LAS unsigned char* lds, const GlaArgs& A, int t0, int h, int tid) {
;     LAS float* GC = (LAS float*)(lds + GL_GC);
;     { const int d = tid & 63, i0 = tid >> 6; float au[16]; const float ab = A.abias[h * 64 + d];
; #pragma unroll
;       for (int j = 0; j < 16; ++j) au[j] = A.aup[j * 256 + h * 64 + d];
;       u32x4 al0[8], al1[8];
; #pragma unroll
;       for (int e = 0; e < 8; ++e) { const u32x4* ap = (const u32x4*)(A.Ug + (size_t)(t0 + i0 + 8 * e) * 1792 + 1024); al0[e] = ap[0]; al1[e] = ap[1]; }
; #pragma unroll
;       for (int e = 0; e < 8; ++e) { const int i = i0 + 8 * e; const u32x4 a0 = al0[e], a1 = al1[e];
;           float x = ab;
;           x += bflo(a0.x) * au[0] + bfhi(a0.x) * au[1] + bflo(a0.y) * au[2] + bfhi(a0.y) * au[3] + bflo(a0.z) * au[4] + bfhi(a0.z) * au[5] + bflo(a0.w) * au[6] + bfhi(a0.w) * au[7];
;           x += bflo(a1.x) * au[8] + bfhi(a1.x) * au[9] + bflo(a1.y) * au[10] + bfhi(a1.y) * au[11] + bflo(a1.z) * au[12] + bfhi(a1.z) * au[13] + bflo(a1.w) * au[14] + bfhi(a1.w) * au[15];
;           const float ls = fminf(x, 0.f) - __logf(1.f + __expf(-fabsf(x)));
;           GC[i * 65 + d] = ls * (1.0f / 16.0f); } }
;     __syncthreads();
;     { const int lane = tid & 63, wave = tid >> 6;
; #pragma unroll
;       for (int dd = 0; dd < 8; ++dd) { const int d = wave * 8 + dd; float x = GC[lane * 65 + d];
; #pragma unroll
;           for (int o = 1; o < 64; o <<= 1) { const float y = __shfl_up(x, o); if (lane >= o) x += y; }
;           GC[lane * 65 + d] = x; } }
;     __syncthreads();
; }
; __device__ __forceinline__ void gla_a_tile(LAS unsigned char* lds, const GlaArgs& A, int tile, int tid) {
;     const int bh = tile >> 6, n = tile & 63, b = bh >> 2, h = bh & 3, t0 = b * SEQ + n * 64, s0 = n * 64;
;     LAS float* GC = (LAS float*)(lds + GL_GC); LAS bf16_t* KDT = (LAS bf16_t*)(lds + GL_T0); LAS bf16_t* VT = (LAS bf16_t*)(lds + GL_VT);
;     gla_gcum(lds, A, t0, h, tid);
;     { const int cc = (tid & 63) * 4, i0 = tid >> 6;
;       if (cc >= 64) { f32x4 o[8]; const int c0 = (cc < 128) ? 256 + h * 64 + (cc - 64) : 512 + h * 128 + (cc - 128);
;           gla_conv8(o, A.Ug, A.conv, t0, s0, i0, c0);
;           if (cc < 128) { const int d = cc - 64;
; #pragma unroll
;               for (int e = 0; e < 8; ++e) { const int i = i0 + 8 * e;
; #pragma unroll
.LBB0_188:
	s_andn2_b64 vcc, exec, s[4:5]
	s_cbranch_vccnz .LBB0_370
	v_readlane_b32 s6, v252, 40
	v_readlane_b32 s7, v252, 41
	s_mov_b64 s[4:5], -1
	s_and_b64 vcc, exec, s[6:7]
	s_cbranch_vccz .LBB0_321
	s_mov_b32 s16, 0
	s_ashr_i32 s17, s16, 31
	s_add_u32 s4, s92, s16
	s_addc_u32 s5, s93, s17
	v_mov_b32_e32 v2, v232
	s_mov_b32 s10, s2
	s_mov_b32 s6, s3
	s_add_u32 s24, s4, 0x19900000
	v_readlane_b32 s36, v252, 24
	s_addc_u32 s25, s5, 0
	s_lshl_b64 s[4:5], s[16:17], 2
	v_readlane_b32 s48, v252, 36
	v_readlane_b32 s49, v252, 37
	s_add_u32 s6, s48, s4
	s_addc_u32 s7, s49, s5
	s_and_b32 s26, s1, 0xffff
	s_lshl_b32 s27, s26, 12
	s_lshl_b32 s11, s26, 14
	s_add_u32 s8, s6, s11
	v_readlane_b32 s50, v252, 38
	s_addc_u32 s9, s7, 0
	v_readlane_b32 s51, v252, 39
	s_add_u32 s6, s50, s4
	s_addc_u32 s7, s51, s5
	v_readlane_b32 s37, v252, 25
	v_readlane_b32 s38, v252, 26
	v_readlane_b32 s39, v252, 27
	v_readlane_b32 s40, v252, 28
	v_readlane_b32 s41, v252, 29
	v_readlane_b32 s42, v252, 30
	v_readlane_b32 s43, v252, 31
	v_readlane_b32 s44, v252, 32
	v_readlane_b32 s45, v252, 33
	v_readlane_b32 s46, v252, 34
	v_readlane_b32 s47, v252, 35
	s_add_u32 s6, s6, s11
	s_addc_u32 s7, s7, 0
	v_readlane_b32 s36, v253, 39
	v_readlane_b32 s37, v253, 40
	s_add_u32 s4, s36, s4
	s_addc_u32 s5, s37, s5
	s_lshl_b32 s28, s26, 8
	s_lshl_b32 s11, s26, 10
	s_add_u32 s4, s4, s11
	s_addc_u32 s5, s5, 0
	s_add_i32 s11, s10, 0x7fffff80
	s_lshl_b32 s13, s10, 1
	s_lshr_b32 s12, s11, 5
	s_and_b32 s13, s13, 12
	s_add_i32 s13, s13, s12
	s_bfe_u32 s11, s11, 0x20005
	s_bfe_i32 s14, s13, 0x1a0000
	s_lshl_b32 s12, s13, 10
	v_and_b32_e32 v8, 63, v2
	s_lshl_b32 s13, s11, 6
	v_or_b32_e32 v0, s13, v8
	v_lshlrev_b32_e32 v0, 2, v0
	v_lshl_add_u64 v[58:59], s[4:5], 0, v[0:1]
	v_lshl_add_u64 v[60:61], s[6:7], 0, v[0:1]
	s_mov_b64 s[4:5], 0x1400
	v_lshl_add_u64 v[64:65], v[60:61], 0, s[4:5]
	s_mov_b64 s[4:5], 0x1800
	v_lshl_add_u64 v[66:67], v[60:61], 0, s[4:5]
	s_mov_b64 s[4:5], 0x1c00
	v_lshl_add_u64 v[68:69], v[60:61], 0, s[4:5]
	s_mov_b64 s[4:5], 0x2400
	v_lshl_add_u64 v[72:73], v[60:61], 0, s[4:5]
	s_mov_b64 s[4:5], 0x2800
	v_lshl_add_u64 v[74:75], v[60:61], 0, s[4:5]
	s_mov_b64 s[4:5], 0x2c00
	v_lshl_add_u64 v[76:77], v[60:61], 0, s[4:5]
	s_mov_b64 s[4:5], 0x3400
	v_and_b32_e32 v118, 64, v237
	v_add_u32_e32 v0, -1, v237
	v_lshl_add_u64 v[80:81], v[60:61], 0, s[4:5]
	s_mov_b64 s[4:5], 0x3800
	v_cmp_lt_i32_e32 vcc, v0, v118
	v_lshl_add_u64 v[82:83], v[60:61], 0, s[4:5]
	s_mov_b64 s[4:5], 0x3c00
	v_cndmask_b32_e32 v0, v0, v237, vcc
	v_lshl_add_u64 v[84:85], v[60:61], 0, s[4:5]
	v_ashrrev_i32_e32 v9, 6, v2
	s_movk_i32 s4, 0x104
	v_lshlrev_b32_e32 v126, 2, v0
	v_add_u32_e32 v0, -2, v237
	v_mul_lo_u32 v120, v9, s4
	v_cmp_lt_i32_e64 s[4:5], v0, v118
	v_lshlrev_b32_e32 v10, 2, v8
	s_ashr_i32 s15, s14, 31
	v_cndmask_b32_e64 v0, v0, v237, s[4:5]
	v_lshlrev_b32_e32 v127, 2, v0
	v_add_u32_e32 v0, -4, v237
	v_cmp_lt_i32_e64 s[6:7], v0, v118
	s_lshl_b64 s[18:19], s[14:15], 21
	s_and_b32 s12, s12, 0xfffff000
	v_cndmask_b32_e64 v0, v0, v237, s[6:7]
	v_lshlrev_b32_e32 v128, 2, v0
	v_add_u32_e32 v0, -8, v237
	v_cmp_lt_i32_e64 s[6:7], v0, v118
	v_readlane_b32 s20, v254, 42
	v_readlane_b32 s38, v253, 41
	s_waitcnt lgkmcnt(0)
; __device__ __forceinline__ void gla_gcum(LAS unsigned char* lds, const GlaArgs& A, int t0, int h, int tid) {
;     LAS float* GC = (LAS float*)(lds + GL_GC);
;     { const int d = tid & 63, i0 = tid >> 6; float au[16]; const float ab = A.abias[h * 64 + d];
; #pragma unroll
;       for (int j = 0; j < 16; ++j) au[j] = A.aup[j * 256 + h * 64 + d];
;       u32x4 al0[8], al1[8];
; #pragma unroll
;       for (int e = 0; e < 8; ++e) { const u32x4* ap = (const u32x4*)(A.Ug + (size_t)(t0 + i0 + 8 * e) * 1792 + 1024); al0[e] = ap[0]; al1[e] = ap[1]; }
; #pragma unroll
;       for (int e = 0; e < 8; ++e) { const int i = i0 + 8 * e; const u32x4 a0 = al0[e], a1 = al1[e];
;           float x = ab;
;           x += bflo(a0.x) * au[0] + bfhi(a0.x) * au[1] + bflo(a0.y) * au[2] + bfhi(a0.y) * au[3] + bflo(a0.z) * au[4] + bfhi(a0.z) * au[5] + bflo(a0.w) * au[6] + bfhi(a0.w) * au[7];
;           x += bflo(a1.x) * au[8] + bfhi(a1.x) * au[9] + bflo(a1.y) * au[10] + bfhi(a1.y) * au[11] + bflo(a1.z) * au[12] + bfhi(a1.z) * au[13] + bflo(a1.w) * au[14] + bfhi(a1.w) * au[15];
;           const float ls = fminf(x, 0.f) - __logf(1.f + __expf(-fabsf(x)));
;           GC[i * 65 + d] = ls * (1.0f / 16.0f); } }
;     __syncthreads();
;     { const int lane = tid & 63, wave = tid >> 6;
; #pragma unroll
;       for (int dd = 0; dd < 8; ++dd) { const int d = wave * 8 + dd; float x = GC[lane * 65 + d];
; #pragma unroll
;           for (int o = 1; o < 64; o <<= 1) { const float y = __shfl_up(x, o); if (lane >= o) x += y; }
;           GC[lane * 65 + d] = x; } }
;     __syncthreads();
; }
; __device__ __forceinline__ void gla_a_tile(LAS unsigned char* lds, const GlaArgs& A, int tile, int tid) {
;     const int bh = tile >> 6, n = tile & 63, b = bh >> 2, h = bh & 3, t0 = b * SEQ + n * 64, s0 = n * 64;
;     LAS float* GC = (LAS float*)(lds + GL_GC); LAS bf16_t* KDT = (LAS bf16_t*)(lds + GL_T0); LAS bf16_t* VT = (LAS bf16_t*)(lds + GL_VT);
;     gla_gcum(lds, A, t0, h, tid);
;     { const int cc = (tid & 63) * 4, i0 = tid >> 6;
;       if (cc >= 64) { f32x4 o[8]; const int c0 = (cc < 128) ? 256 + h * 64 + (cc - 64) : 512 + h * 128 + (cc - 128);
;           gla_conv8(o, A.Ug, A.conv, t0, s0, i0, c0);
;           if (cc < 128) { const int d = cc - 64;
; #pragma unroll
;               for (int e = 0; e < 8; ++e) { const int i = i0 + 8 * e;
; #pragma unroll
	v_cndmask_b32_e64 v3, v0, v237, s[6:7]
	v_add_u32_e32 v0, -16, v237
	v_cmp_lt_i32_e64 s[6:7], v0, v118
	v_lshlrev_b32_e32 v129, 2, v3
	v_ashrrev_i32_e32 v3, 31, v2
	v_cndmask_b32_e64 v4, v0, v237, s[6:7]
	v_subrev_u32_e32 v0, 32, v237
	v_cmp_lt_i32_e64 s[6:7], v0, v118
	v_lshlrev_b32_e32 v130, 2, v4
	v_lshlrev_b32_e32 v4, 4, v9
	v_cndmask_b32_e64 v5, v0, v237, s[6:7]
	s_lshl_b32 s7, s11, 7
	s_add_i32 s6, s13, 0xc0
	s_addk_i32 s7, 0x180
	v_mov_b32_e32 v0, s7
	v_mov_b32_e32 v6, s6
	v_cmp_gt_u32_e64 s[6:7], 32, v8
	v_lshlrev_b32_e32 v131, 2, v5
	v_ashrrev_i32_e32 v5, 31, v4
	v_cndmask_b32_e64 v0, v0, v6, s[6:7]
	v_add_u32_e32 v13, v0, v10
	v_lshlrev_b32_e32 v0, 2, v13
	v_lshl_add_u64 v[86:87], s[8:9], 0, v[0:1]
	s_lshl_b64 s[8:9], s[14:15], 14
	s_and_b32 s14, s10, 1
	s_bfe_u32 s15, s10, 0x20003
	s_lshl_b32 s11, s14, 11
	s_lshl_b32 s10, s15, 9
	s_or_b32 s13, s11, s10
	s_lshl_b32 s10, s13, 2
	v_readlane_b32 s11, v254, 41
	s_add_u32 s11, s11, s16
	s_addc_u32 s20, s20, s17
	s_add_u32 s10, s11, s10
	s_addc_u32 s11, s20, 0
	s_add_u32 s10, s10, s8
	s_addc_u32 s11, s11, s9
	s_lshl_b32 s14, s14, 12
	s_lshl_b32 s15, s15, 10
	s_or_b32 s62, s14, s15
	v_and_b32_e32 v0, 15, v2
	v_lshl_add_u64 v[6:7], v[4:5], 0, s[62:63]
	v_or_b32_e32 v6, v6, v0
	v_lshlrev_b64 v[6:7], 8, v[6:7]
	s_or_b32 s30, s13, s12
	v_lshl_add_u64 v[6:7], s[18:19], 0, v[6:7]
	v_readlane_b32 s18, v254, 43
	v_lshl_add_u64 v[88:89], v[2:3], 2, s[10:11]
	s_add_u32 s18, s18, s16
	v_readlane_b32 s16, v254, 44
	v_and_b32_e32 v3, 48, v2
	s_addc_u32 s19, s16, s17
	v_or_b32_e32 v6, v6, v3
	v_or_b32_e32 v5, v4, v0
	v_add_u32_e32 v4, 0, v3
	s_movk_i32 s20, 0x90
	v_readlane_b32 s39, v253, 42
	v_readlane_b32 s40, v253, 43
	v_readlane_b32 s41, v253, 44
	v_readlane_b32 s42, v253, 45
	v_readlane_b32 s43, v253, 46
	v_readlane_b32 s44, v253, 47
	v_readlane_b32 s45, v253, 48
	v_readlane_b32 s46, v253, 49
	v_readlane_b32 s47, v253, 50
	v_readlane_b32 s48, v253, 51
	v_readlane_b32 s49, v253, 52
	v_readlane_b32 s50, v253, 53
	v_readlane_b32 s51, v253, 54
	v_add_u32_e32 v119, 0, v10
	v_lshl_add_u64 v[90:91], s[18:19], 0, v[6:7]
	v_mad_u64_u32 v[92:93], s[20:21], v5, s20, v[4:5]
	v_subrev_u32_e32 v6, 64, v10
	s_mov_b64 s[22:23], 0x2000
	s_mov_b64 s[34:35], 0x3000
	v_lshl_add_u32 v11, v8, 8, v119
	v_lshlrev_b32_e32 v12, 5, v9
	v_mul_u32_u24_e32 v3, 0x90, v0
	v_lshlrev_b32_e32 v0, 1, v13
	v_lshl_add_u32 v5, v9, 1, 0
	s_movk_i32 s20, 0x240
	v_lshl_add_u32 v93, v8, 4, 0
	v_mul_i32_i24_e32 v6, 0x90, v6
	v_readlane_b32 s36, v252, 43
	v_readlane_b32 s38, v252, 45
	v_readlane_b32 s40, v252, 47
	v_readlane_b32 s42, v252, 49
	v_readlane_b32 s44, v252, 51
	v_readlane_b32 s46, v252, 53
	v_readlane_b32 s48, v252, 55
	v_readlane_b32 s50, v252, 57
	v_readlane_b32 s52, v252, 59
	s_mov_b32 s29, 0
	v_lshl_add_u64 v[62:63], v[60:61], 0, s[60:61]
	v_lshl_add_u64 v[70:71], v[60:61], 0, s[22:23]
	v_lshl_add_u64 v[78:79], v[60:61], 0, s[34:35]
	v_cmp_eq_u32_e32 vcc, 0, v8
	v_cmp_gt_u32_e64 s[4:5], 2, v8
	v_cmp_gt_u32_e64 s[8:9], 4, v8
	v_cmp_gt_u32_e64 s[10:11], 8, v8
	v_add_u32_e32 v121, s13, v9
	v_cmp_gt_u32_e64 s[12:13], 16, v8
	v_cmp_lt_u32_e64 s[14:15], 31, v8
	v_cmp_lt_u32_e64 s[16:17], 15, v8
	v_cmp_gt_i32_e64 s[18:19], 64, v2
	v_lshl_add_u64 v[94:95], v[86:87], 0, s[60:61]
	v_lshl_add_u64 v[96:97], v[86:87], 0, s[22:23]
	v_lshl_add_u64 v[98:99], v[86:87], 0, s[34:35]
	v_lshl_add_u64 v[100:101], s[24:25], 0, v[0:1]
	v_mad_u32_u24 v0, v8, s20, v5
	v_add_u32_e32 v122, 0xffffff00, v93
	v_add_u32_e32 v123, 0x820, v120
	v_lshl_add_u32 v124, v2, 2, 0
	v_add_u32_e32 v125, s30, v9
	v_add_u32_e32 v132, v11, v12
	v_add_u32_e32 v133, v5, v6
	v_add_u32_e32 v134, v4, v3
	v_readlane_b32 s37, v252, 44
	v_readlane_b32 s39, v252, 46
	v_readlane_b32 s41, v252, 48
	v_readlane_b32 s43, v252, 50
	v_readlane_b32 s45, v252, 52
	v_readlane_b32 s47, v252, 54
	v_readlane_b32 s49, v252, 56
	v_readlane_b32 s51, v252, 58
	v_readlane_b32 s53, v252, 60
	s_branch .LBB0_192
	s_nop 0
	s_nop 0
	s_nop 0
	s_nop 0
	s_nop 0
	s_nop 0
	s_nop 0
	s_nop 0
	s_nop 0
	s_nop 0
	s_nop 0
	s_nop 0
	s_nop 0
	s_nop 0
	s_nop 0
